# v059 SEQ step-loop heads aligned to 256 bytes (code placement)
# speedup vs baseline: 1.0013x; 1.0013x over previous
; #define WAIT_VM(n) do {} while (0)
; #define LAS __attribute__((address_space(3)))
; #define WAIT_VM(n) asm volatile("s_waitcnt vmcnt(" #n ")" ::: "memory")
; #define LDS_BARRIER() do { WAIT_LGKM(0); S_BARRIER(); COMPILER_FENCE(); } while (0)
; template <int KIND>
; DEV void seq_step(const Frame& F, const SeqCtx& C, int n, f32x16& acc, LAS unsigned char* lds) {
;     ...
;     LDS_BARRIER();
; }
; template <int KIND>
; DEV void seq_kind_loop(const Frame& F, const SeqCtx& C, LAS unsigned char* lds) {
;     f32x16 acc;
; #pragma unroll
;     for (int r = 0; r < 16; ++r) acc[r] = 0.f;
;     seq_dma<KIND>(F, C, 0, lds);
;     WAIT_VM(0);
;     LDS_BARRIER();
;     for (int n = 0; n < NCH; ++n) seq_step<KIND>(F, C, n, acc, lds);
.LBB0_897:
	s_waitcnt lgkmcnt(0)
	s_barrier
	s_add_i32 s62, s62, 64
	s_sub_i32 s57, s57, 64
	s_cmpk_lg_i32 s28, 0x44
	s_mov_b32 s63, s28
	s_cbranch_scc0 .LBB0_937
	.p2align	8

; #define WAIT_VM(n) do {} while (0)
; #define LAS __attribute__((address_space(3)))
; #define WAIT_VM(n) asm volatile("s_waitcnt vmcnt(" #n ")" ::: "memory")
; #define LDS_BARRIER() do { WAIT_LGKM(0); S_BARRIER(); COMPILER_FENCE(); } while (0)
; template <int KIND>
; DEV void seq_step(const Frame& F, const SeqCtx& C, int n, f32x16& acc, LAS unsigned char* lds) {
;     ...
;     LDS_BARRIER();
; }
; template <int KIND>
; DEV void seq_kind_loop(const Frame& F, const SeqCtx& C, LAS unsigned char* lds) {
;     f32x16 acc;
; #pragma unroll
;     for (int r = 0; r < 16; ++r) acc[r] = 0.f;
;     seq_dma<KIND>(F, C, 0, lds);
;     WAIT_VM(0);
;     LDS_BARRIER();
;     for (int n = 0; n < NCH; ++n) seq_step<KIND>(F, C, n, acc, lds);
.LBB0_958:
	s_waitcnt lgkmcnt(0)
	s_barrier
	s_add_i32 s83, s83, 64
	s_sub_i32 s6, s6, 64
	s_cmpk_eq_i32 s84, 0x44
	s_mov_b32 s88, s84
	s_cbranch_scc1 .LBB0_992
	.p2align	8

; #define WAIT_VM(n) do {} while (0)
; #define LAS __attribute__((address_space(3)))
; #define WAIT_VM(n) asm volatile("s_waitcnt vmcnt(" #n ")" ::: "memory")
; #define LDS_BARRIER() do { WAIT_LGKM(0); S_BARRIER(); COMPILER_FENCE(); } while (0)
; template <int KIND>
; DEV void seq_step(const Frame& F, const SeqCtx& C, int n, f32x16& acc, LAS unsigned char* lds) {
;     ...
;     LDS_BARRIER();
; }
; template <int KIND>
; DEV void seq_kind_loop(const Frame& F, const SeqCtx& C, LAS unsigned char* lds) {
;     f32x16 acc;
; #pragma unroll
;     for (int r = 0; r < 16; ++r) acc[r] = 0.f;
;     seq_dma<KIND>(F, C, 0, lds);
;     WAIT_VM(0);
;     LDS_BARRIER();
;     for (int n = 0; n < NCH; ++n) seq_step<KIND>(F, C, n, acc, lds);
.LBB0_1012:
	s_waitcnt lgkmcnt(0)
	s_barrier
	s_add_i32 s57, s57, 64
	s_sub_i32 s6, s6, 64
	s_cmpk_eq_i32 s64, 0x44
	s_mov_b32 s65, s64
	s_cbranch_scc1 .LBB0_814
	.p2align	8

; #define WAIT_VM(n) do {} while (0)
; #define LAS __attribute__((address_space(3)))
; #define WAIT_VM(n) asm volatile("s_waitcnt vmcnt(" #n ")" ::: "memory")
; #define LDS_BARRIER() do { WAIT_LGKM(0); S_BARRIER(); COMPILER_FENCE(); } while (0)
; template <int KIND>
; DEV void seq_step(const Frame& F, const SeqCtx& C, int n, f32x16& acc, LAS unsigned char* lds) {
;     ...
;     LDS_BARRIER();
; }
; template <int KIND>
; DEV void seq_kind_loop(const Frame& F, const SeqCtx& C, LAS unsigned char* lds) {
;     f32x16 acc;
; #pragma unroll
;     for (int r = 0; r < 16; ++r) acc[r] = 0.f;
;     seq_dma<KIND>(F, C, 0, lds);
;     WAIT_VM(0);
;     LDS_BARRIER();
;     for (int n = 0; n < NCH; ++n) seq_step<KIND>(F, C, n, acc, lds);
.LBB0_1117:
	s_waitcnt lgkmcnt(0)
	s_barrier
	s_add_i32 s73, s73, 64
	s_sub_i32 s67, s67, 64
	s_cmpk_lg_i32 s74, 0x44
	s_mov_b32 s75, s74
	s_cbranch_scc0 .LBB0_1157
	.p2align	8
